# GEMM k-loops: 11 of 16 LDS-DMA per two K-tiles use the saddr form (SGPR base + 32-bit lane offset), their 64-bit VALU address adds removed; on top of the unrolled-by-4 attention loop
# speedup vs baseline: 1.0134x; 1.0030x over previous
; #define PG8_STAGE(bufoff, gbase, voff) do { _Pragma("unroll") for (int _i = 0; _i < 2; ++_i) \
;         __builtin_amdgcn_global_load_lds((const unsigned*)((const char*)(gbase) + (voff)[_i]), (PG8_LAS unsigned*)(lds + (bufoff) + ldsw + _i * 8192), 16, 0, 0); } while (0)
; #define PG8_LDA(dst, b, h) do { _Pragma("unroll") for (int m = 0; m < 4; ++m) _Pragma("unroll") for (int k = 0; k < 2; ++k) dst[m][k] = *(const PG8_LAS bf16x8*)(lds + PG8_SA(b, h) + aoff + m * 2048 + k * 1024); } while (0)
; #define PG8_LDB(dst, b, h) do { _Pragma("unroll") for (int n = 0; n < 2; ++n) _Pragma("unroll") for (int k = 0; k < 2; ++k) dst[n][k] = *(const PG8_LAS bf16x8*)(lds + PG8_SB(b, h) + boff + n * 2048 + k * 1024); } while (0)
; #define PG8_MMA(ai, bj, At, Bt) do { __builtin_amdgcn_s_setprio(1); _Pragma("unroll") for (int m = 0; m < 4; ++m) _Pragma("unroll") for (int n = 0; n < 2; ++n) _Pragma("unroll") for (int k = 0; k < 2; ++k) \
;         acc[ai][bj][m][n] = __builtin_amdgcn_mfma_f32_16x16x32_bf16(Bt[n][k], At[m][k], acc[ai][bj][m][n], 0, 0, 0); __builtin_amdgcn_s_setprio(0); } while (0)
; #define PG8_WAIT_V(n) asm volatile("s_waitcnt vmcnt(" #n ")" ::: "memory")
; #define PG8_BAR __builtin_amdgcn_s_barrier()
; template <class Epi, class Sched, bool ALIGN_EPI = false, bool SP2 = false>
; __device__ __forceinline__ void gemm_phase(PG8_LAS unsigned char* lds, const Gemm g, const Sched& S, const Epi& E, int wv) {
;     ...
;         for (int t = 0; t < nt; t += 2) {
;             const bool last = (t == nt - 2);
;             const char* a1 = cA + (size_t)(t + 1) * kstep;
;             const char* a2 = last ? nA : cA + (size_t)(t + 2) * kstep; const char* b2 = last ? nB : cB + (size_t)(t + 2) * kstep;
;             const char* a3 = a2 + kstep; const char* b3 = b2 + kstep;
;             if (last && has_next) S.a_ready(nxt);
;             if constexpr (SP2) {
;             PG8_LDB(B0, 0, 0); PG8_LDB(B1, 0, 1); PG8_SCHED; PG8_LDA(At, 0, 0); PG8_STAGE(PG8_SA(1, 1), a1 + hstep, voffA);
;             PG8_WAIT_V(8); PG8_WAIT_L(0); PG8_BAR; PG8_MMA(0, 0, At, B0); PG8_MMA(0, 1, At, B1); PG8_BAR; PG8_SCHED;
;             PG8_LDA(At, 0, 1); PG8_STAGE(PG8_SB(0, 0), b2, voffB); PG8_STAGE(PG8_SB(0, 1), b2 + hstep, voffB); PG8_STAGE(PG8_SA(0, 0), a2, voffA);
;             PG8_WAIT_V(8); PG8_WAIT_L(0); PG8_BAR; PG8_MMA(1, 0, At, B0); PG8_MMA(1, 1, At, B1); PG8_BAR; PG8_SCHED;
.LBB0_120:
	s_add_u32 s44, s34, 0xfff80080
	s_addc_u32 s45, s35, -1
	s_add_i32 s52, 0, 0x10000
	s_cmp_eq_u32 s51, 28
	s_cselect_b32 s47, s7, s45
	s_cselect_b32 s46, s21, s44
	s_cselect_b32 s45, s19, s50
	s_cselect_b32 s44, s48, s49
	s_add_i32 s54, 0, 0x14000
	v_add_u32_e32 v152, s52, v189
	v_add_u32_e32 v168, s54, v189
	ds_read_b128 v[128:131], v152
	ds_read_b128 v[132:135], v152 offset:1024
	ds_read_b128 v[148:151], v152 offset:2048
	ds_read_b128 v[152:155], v152 offset:3072
	s_nop 0
	ds_read_b128 v[156:159], v168
	ds_read_b128 v[160:163], v168 offset:1024
	ds_read_b128 v[164:167], v168 offset:2048
	ds_read_b128 v[168:171], v168 offset:3072
	s_add_i32 m0, s11, 0xc000
	ds_read_b128 v[172:175], v192
	ds_read_b128 v[194:197], v192 offset:1024
	ds_read_b128 v[198:201], v192 offset:2048
	ds_read_b128 v[202:205], v192 offset:3072
	ds_read_b128 v[206:209], v192 offset:4096
	ds_read_b128 v[210:213], v192 offset:5120
	ds_read_b128 v[214:217], v192 offset:6144
	ds_read_b128 v[218:221], v192 offset:7168
	global_load_lds_dwordx4 v144, s[34:35]
	s_add_i32 m0, s11, 0xe000
	s_nop 0
	global_load_lds_dwordx4 v146, s[34:35]
	s_waitcnt vmcnt(8)
	s_waitcnt lgkmcnt(0)
	s_barrier
	s_setprio 1
	s_waitcnt lgkmcnt(0)
	v_mfma_f32_16x16x32_bf16 v[124:127], v[128:131], v[172:175], v[124:127]
	v_mfma_f32_16x16x32_bf16 v[120:123], v[148:151], v[172:175], v[120:123]
	v_mfma_f32_16x16x32_bf16 v[112:115], v[128:131], v[198:201], v[112:115]
	v_mfma_f32_16x16x32_bf16 v[104:107], v[148:151], v[198:201], v[104:107]
	v_mfma_f32_16x16x32_bf16 v[96:99], v[128:131], v[206:209], v[96:99]
	v_mfma_f32_16x16x32_bf16 v[88:91], v[148:151], v[206:209], v[88:91]
	v_mfma_f32_16x16x32_bf16 v[80:83], v[128:131], v[214:217], v[80:83]
	v_mfma_f32_16x16x32_bf16 v[72:75], v[148:151], v[214:217], v[72:75]
	v_mfma_f32_16x16x32_bf16 v[124:127], v[132:135], v[194:197], v[124:127]
	v_mfma_f32_16x16x32_bf16 v[120:123], v[152:155], v[194:197], v[120:123]
	v_mfma_f32_16x16x32_bf16 v[112:115], v[132:135], v[202:205], v[112:115]
	v_mfma_f32_16x16x32_bf16 v[104:107], v[152:155], v[202:205], v[104:107]
	v_mfma_f32_16x16x32_bf16 v[96:99], v[132:135], v[210:213], v[96:99]
	v_mfma_f32_16x16x32_bf16 v[88:91], v[152:155], v[210:213], v[88:91]
	v_mfma_f32_16x16x32_bf16 v[80:83], v[132:135], v[218:221], v[80:83]
	v_mfma_f32_16x16x32_bf16 v[72:75], v[152:155], v[218:221], v[72:75]
	s_setprio 0
	s_setprio 1
	v_mfma_f32_16x16x32_bf16 v[116:119], v[156:159], v[172:175], v[116:119]
	v_mfma_f32_16x16x32_bf16 v[108:111], v[164:167], v[172:175], v[108:111]
	v_mfma_f32_16x16x32_bf16 v[100:103], v[156:159], v[198:201], v[100:103]
	v_mfma_f32_16x16x32_bf16 v[92:95], v[164:167], v[198:201], v[92:95]
	v_mfma_f32_16x16x32_bf16 v[84:87], v[156:159], v[206:209], v[84:87]
	v_mfma_f32_16x16x32_bf16 v[76:79], v[164:167], v[206:209], v[76:79]
	v_mfma_f32_16x16x32_bf16 v[68:71], v[156:159], v[214:217], v[68:71]
	v_mfma_f32_16x16x32_bf16 v[64:67], v[164:167], v[214:217], v[64:67]
	v_mfma_f32_16x16x32_bf16 v[116:119], v[160:163], v[194:197], v[116:119]
	v_mfma_f32_16x16x32_bf16 v[108:111], v[168:171], v[194:197], v[108:111]
	v_mfma_f32_16x16x32_bf16 v[100:103], v[160:163], v[202:205], v[100:103]
	v_mfma_f32_16x16x32_bf16 v[92:95], v[168:171], v[202:205], v[92:95]
	v_mfma_f32_16x16x32_bf16 v[84:87], v[160:163], v[210:213], v[84:87]
	v_mfma_f32_16x16x32_bf16 v[76:79], v[168:171], v[210:213], v[76:79]
	v_mfma_f32_16x16x32_bf16 v[68:71], v[160:163], v[218:221], v[68:71]
	v_mfma_f32_16x16x32_bf16 v[64:67], v[168:171], v[218:221], v[64:67]
	s_setprio 0
	s_barrier
	s_add_i32 s52, s52, s0
	s_mov_b32 m0, s52
	ds_read_b128 v[172:175], v192 offset:16384
	ds_read_b128 v[194:197], v192 offset:17408
	ds_read_b128 v[198:201], v192 offset:18432
	ds_read_b128 v[202:205], v192 offset:19456
	ds_read_b128 v[206:209], v192 offset:20480
	ds_read_b128 v[210:213], v192 offset:21504
	ds_read_b128 v[214:217], v192 offset:22528
	ds_read_b128 v[218:221], v192 offset:23552
	global_load_lds_dwordx4 v176, s[44:45]
	s_add_i32 m0, s52, 0x2000
	s_add_u32 s52, s44, 0x80000
	s_addc_u32 s53, s45, 0
	s_add_i32 s54, s54, s0
	global_load_lds_dwordx4 v136, s[44:45]
	s_mov_b32 m0, s54
	v_lshl_add_u64 v[184:185], s[46:47], 0, v[138:139]
	global_load_lds_dwordx4 v176, s[52:53]
	s_add_i32 m0, s54, 0x2000
	s_nop 0
	global_load_lds_dwordx4 v136, s[52:53]
	v_lshl_add_u64 v[182:183], s[46:47], 0, v[140:141]
	s_mov_b32 m0, s11
	s_nop 0
	global_load_lds_dwordx4 v[182:183], off
	s_mov_b32 m0, s22
	s_nop 0
	global_load_lds_dwordx4 v[184:185], off
	s_waitcnt vmcnt(8)
	s_waitcnt lgkmcnt(0)
	s_barrier
; #define PG8_STAGE(bufoff, gbase, voff) do { _Pragma("unroll") for (int _i = 0; _i < 2; ++_i) \
;         __builtin_amdgcn_global_load_lds((const unsigned*)((const char*)(gbase) + (voff)[_i]), (PG8_LAS unsigned*)(lds + (bufoff) + ldsw + _i * 8192), 16, 0, 0); } while (0)
; #define PG8_LDA(dst, b, h) do { _Pragma("unroll") for (int m = 0; m < 4; ++m) _Pragma("unroll") for (int k = 0; k < 2; ++k) dst[m][k] = *(const PG8_LAS bf16x8*)(lds + PG8_SA(b, h) + aoff + m * 2048 + k * 1024); } while (0)
; #define PG8_LDB(dst, b, h) do { _Pragma("unroll") for (int n = 0; n < 2; ++n) _Pragma("unroll") for (int k = 0; k < 2; ++k) dst[n][k] = *(const PG8_LAS bf16x8*)(lds + PG8_SB(b, h) + boff + n * 2048 + k * 1024); } while (0)
; #define PG8_MMA(ai, bj, At, Bt) do { __builtin_amdgcn_s_setprio(1); _Pragma("unroll") for (int m = 0; m < 4; ++m) _Pragma("unroll") for (int n = 0; n < 2; ++n) _Pragma("unroll") for (int k = 0; k < 2; ++k) \
;         acc[ai][bj][m][n] = __builtin_amdgcn_mfma_f32_16x16x32_bf16(Bt[n][k], At[m][k], acc[ai][bj][m][n], 0, 0, 0); __builtin_amdgcn_s_setprio(0); } while (0)
; #define PG8_WAIT_V(n) asm volatile("s_waitcnt vmcnt(" #n ")" ::: "memory")
; #define PG8_WAIT_L(n) asm volatile("s_waitcnt lgkmcnt(" #n ")" ::: "memory")
; #define PG8_BAR __builtin_amdgcn_s_barrier()
; #define PG8_SCHED __builtin_amdgcn_sched_barrier(0)
; template <class Epi, class Sched, bool ALIGN_EPI = false, bool SP2 = false>
; __device__ __forceinline__ void gemm_phase(PG8_LAS unsigned char* lds, const Gemm g, const Sched& S, const Epi& E, int wv) {
;     ...
;             PG8_WAIT_V(8); PG8_WAIT_L(0); PG8_BAR; PG8_MMA(1, 0, At, B0); PG8_MMA(1, 1, At, B1); PG8_BAR; PG8_SCHED;
;             PG8_LDB(B0, 1, 0); PG8_LDB(B1, 1, 1); PG8_SCHED; PG8_LDA(At, 1, 0); PG8_STAGE(PG8_SA(0, 1), a2 + hstep, voffA);
;             PG8_WAIT_V(8); PG8_WAIT_L(0); PG8_BAR; PG8_MMA(0, 0, At, B0); PG8_MMA(0, 1, At, B1); PG8_BAR; PG8_SCHED;
	s_setprio 1
	s_waitcnt lgkmcnt(0)
	v_mfma_f32_16x16x32_bf16 v[60:63], v[128:131], v[172:175], v[60:63]
	v_mfma_f32_16x16x32_bf16 v[56:59], v[148:151], v[172:175], v[56:59]
	v_mfma_f32_16x16x32_bf16 v[48:51], v[128:131], v[198:201], v[48:51]
	v_mfma_f32_16x16x32_bf16 v[40:43], v[148:151], v[198:201], v[40:43]
	v_mfma_f32_16x16x32_bf16 v[32:35], v[128:131], v[206:209], v[32:35]
	v_mfma_f32_16x16x32_bf16 v[24:27], v[148:151], v[206:209], v[24:27]
	v_mfma_f32_16x16x32_bf16 v[16:19], v[128:131], v[214:217], v[16:19]
	v_mfma_f32_16x16x32_bf16 v[8:11], v[148:151], v[214:217], v[8:11]
	v_mfma_f32_16x16x32_bf16 v[60:63], v[132:135], v[194:197], v[60:63]
	v_mfma_f32_16x16x32_bf16 v[56:59], v[152:155], v[194:197], v[56:59]
	v_mfma_f32_16x16x32_bf16 v[48:51], v[132:135], v[202:205], v[48:51]
	v_mfma_f32_16x16x32_bf16 v[40:43], v[152:155], v[202:205], v[40:43]
	v_mfma_f32_16x16x32_bf16 v[32:35], v[132:135], v[210:213], v[32:35]
	v_mfma_f32_16x16x32_bf16 v[24:27], v[152:155], v[210:213], v[24:27]
	v_mfma_f32_16x16x32_bf16 v[16:19], v[132:135], v[218:221], v[16:19]
	v_mfma_f32_16x16x32_bf16 v[8:11], v[152:155], v[218:221], v[8:11]
	s_setprio 0
	s_setprio 1
	v_mfma_f32_16x16x32_bf16 v[52:55], v[156:159], v[172:175], v[52:55]
	v_mfma_f32_16x16x32_bf16 v[44:47], v[164:167], v[172:175], v[44:47]
	v_mfma_f32_16x16x32_bf16 v[36:39], v[156:159], v[198:201], v[36:39]
	v_mfma_f32_16x16x32_bf16 v[28:31], v[164:167], v[198:201], v[28:31]
	v_mfma_f32_16x16x32_bf16 v[20:23], v[156:159], v[206:209], v[20:23]
	v_mfma_f32_16x16x32_bf16 v[12:15], v[164:167], v[206:209], v[12:15]
	v_mfma_f32_16x16x32_bf16 v[4:7], v[156:159], v[214:217], v[4:7]
	v_mfma_f32_16x16x32_bf16 v[0:3], v[164:167], v[214:217], v[0:3]
	v_mfma_f32_16x16x32_bf16 v[52:55], v[160:163], v[194:197], v[52:55]
	v_mfma_f32_16x16x32_bf16 v[44:47], v[168:171], v[194:197], v[44:47]
	v_mfma_f32_16x16x32_bf16 v[36:39], v[160:163], v[202:205], v[36:39]
	v_mfma_f32_16x16x32_bf16 v[28:31], v[168:171], v[202:205], v[28:31]
	v_mfma_f32_16x16x32_bf16 v[20:23], v[160:163], v[210:213], v[20:23]
	v_mfma_f32_16x16x32_bf16 v[12:15], v[168:171], v[210:213], v[12:15]
	v_mfma_f32_16x16x32_bf16 v[4:7], v[160:163], v[218:221], v[4:7]
	v_mfma_f32_16x16x32_bf16 v[0:3], v[168:171], v[218:221], v[0:3]
	s_setprio 0
	s_barrier
	s_add_i32 s52, 0, 0x18000
	s_add_i32 s53, 0, 0x1c000
	v_add_u32_e32 v152, s52, v189
	v_add_u32_e32 v168, s53, v189
	ds_read_b128 v[128:131], v152
	ds_read_b128 v[132:135], v152 offset:1024
	ds_read_b128 v[148:151], v152 offset:2048
	ds_read_b128 v[152:155], v152 offset:3072
	ds_read_b128 v[156:159], v168
	ds_read_b128 v[160:163], v168 offset:1024
	ds_read_b128 v[164:167], v168 offset:2048
	ds_read_b128 v[168:171], v168 offset:3072
	s_add_u32 s46, s46, 0x80000
	s_addc_u32 s47, s47, 0
	s_mov_b32 m0, s23
	ds_read_b128 v[172:175], v192 offset:32768
	ds_read_b128 v[194:197], v192 offset:33792
	ds_read_b128 v[198:201], v192 offset:34816
	ds_read_b128 v[202:205], v192 offset:35840
	ds_read_b128 v[206:209], v192 offset:36864
	ds_read_b128 v[210:213], v192 offset:37888
	ds_read_b128 v[214:217], v192 offset:38912
	ds_read_b128 v[218:221], v192 offset:39936
	global_load_lds_dwordx4 v140, s[46:47]
	v_lshl_add_u64 v[186:187], s[46:47], 0, v[138:139]
	s_mov_b32 m0, s24
	s_nop 0
	global_load_lds_dwordx4 v[186:187], off
	s_waitcnt vmcnt(8)
	s_waitcnt lgkmcnt(0)
	s_barrier
	s_setprio 1
	s_waitcnt lgkmcnt(0)
	v_mfma_f32_16x16x32_bf16 v[124:127], v[128:131], v[172:175], v[124:127]
	v_mfma_f32_16x16x32_bf16 v[120:123], v[148:151], v[172:175], v[120:123]
	v_mfma_f32_16x16x32_bf16 v[112:115], v[128:131], v[198:201], v[112:115]
	v_mfma_f32_16x16x32_bf16 v[104:107], v[148:151], v[198:201], v[104:107]
	v_mfma_f32_16x16x32_bf16 v[96:99], v[128:131], v[206:209], v[96:99]
	v_mfma_f32_16x16x32_bf16 v[88:91], v[148:151], v[206:209], v[88:91]
	v_mfma_f32_16x16x32_bf16 v[80:83], v[128:131], v[214:217], v[80:83]
	v_mfma_f32_16x16x32_bf16 v[72:75], v[148:151], v[214:217], v[72:75]
	v_mfma_f32_16x16x32_bf16 v[124:127], v[132:135], v[194:197], v[124:127]
	v_mfma_f32_16x16x32_bf16 v[120:123], v[152:155], v[194:197], v[120:123]
	v_mfma_f32_16x16x32_bf16 v[112:115], v[132:135], v[202:205], v[112:115]
	v_mfma_f32_16x16x32_bf16 v[104:107], v[152:155], v[202:205], v[104:107]
	v_mfma_f32_16x16x32_bf16 v[96:99], v[132:135], v[210:213], v[96:99]
	v_mfma_f32_16x16x32_bf16 v[88:91], v[152:155], v[210:213], v[88:91]
	v_mfma_f32_16x16x32_bf16 v[80:83], v[132:135], v[218:221], v[80:83]
	v_mfma_f32_16x16x32_bf16 v[72:75], v[152:155], v[218:221], v[72:75]
	s_setprio 0
	s_setprio 1
	v_mfma_f32_16x16x32_bf16 v[116:119], v[156:159], v[172:175], v[116:119]
	v_mfma_f32_16x16x32_bf16 v[108:111], v[164:167], v[172:175], v[108:111]
	v_mfma_f32_16x16x32_bf16 v[100:103], v[156:159], v[198:201], v[100:103]
	v_mfma_f32_16x16x32_bf16 v[92:95], v[164:167], v[198:201], v[92:95]
	v_mfma_f32_16x16x32_bf16 v[84:87], v[156:159], v[206:209], v[84:87]
	v_mfma_f32_16x16x32_bf16 v[76:79], v[164:167], v[206:209], v[76:79]
	v_mfma_f32_16x16x32_bf16 v[68:71], v[156:159], v[214:217], v[68:71]
	v_mfma_f32_16x16x32_bf16 v[64:67], v[164:167], v[214:217], v[64:67]
	v_mfma_f32_16x16x32_bf16 v[116:119], v[160:163], v[194:197], v[116:119]
	v_mfma_f32_16x16x32_bf16 v[108:111], v[168:171], v[194:197], v[108:111]
	v_mfma_f32_16x16x32_bf16 v[100:103], v[160:163], v[202:205], v[100:103]
	v_mfma_f32_16x16x32_bf16 v[92:95], v[168:171], v[202:205], v[92:95]
	v_mfma_f32_16x16x32_bf16 v[84:87], v[160:163], v[210:213], v[84:87]
	v_mfma_f32_16x16x32_bf16 v[76:79], v[168:171], v[210:213], v[76:79]
	v_mfma_f32_16x16x32_bf16 v[68:71], v[160:163], v[218:221], v[68:71]
	v_mfma_f32_16x16x32_bf16 v[64:67], v[168:171], v[218:221], v[64:67]
	s_setprio 0
	s_barrier
; #define PG8_STAGE(bufoff, gbase, voff) do { _Pragma("unroll") for (int _i = 0; _i < 2; ++_i) \
;         __builtin_amdgcn_global_load_lds((const unsigned*)((const char*)(gbase) + (voff)[_i]), (PG8_LAS unsigned*)(lds + (bufoff) + ldsw + _i * 8192), 16, 0, 0); } while (0)
; #define PG8_LDA(dst, b, h) do { _Pragma("unroll") for (int m = 0; m < 4; ++m) _Pragma("unroll") for (int k = 0; k < 2; ++k) dst[m][k] = *(const PG8_LAS bf16x8*)(lds + PG8_SA(b, h) + aoff + m * 2048 + k * 1024); } while (0)
; #define PG8_LDB(dst, b, h) do { _Pragma("unroll") for (int n = 0; n < 2; ++n) _Pragma("unroll") for (int k = 0; k < 2; ++k) dst[n][k] = *(const PG8_LAS bf16x8*)(lds + PG8_SB(b, h) + boff + n * 2048 + k * 1024); } while (0)
; template <class Epi, class Sched, bool ALIGN_EPI = false, bool SP2 = false>
; __device__ __forceinline__ void gemm_phase(PG8_LAS unsigned char* lds, const Gemm g, const Sched& S, const Epi& E, int wv) {
;     ...
;         for (int t = 0; t < nt; t += 2) {
;             const bool last = (t == nt - 2);
;             const char* a1 = cA + (size_t)(t + 1) * kstep;
;             const char* a2 = last ? nA : cA + (size_t)(t + 2) * kstep; const char* b2 = last ? nB : cB + (size_t)(t + 2) * kstep;
;             const char* a3 = a2 + kstep; const char* b3 = b2 + kstep;
;             if (last && has_next) S.a_ready(nxt);
;             if constexpr (SP2) {
;             PG8_LDB(B0, 0, 0); PG8_LDB(B1, 0, 1); PG8_SCHED; PG8_LDA(At, 0, 0); PG8_STAGE(PG8_SA(1, 1), a1 + hstep, voffA);
;             PG8_WAIT_V(8); PG8_WAIT_L(0); PG8_BAR; PG8_MMA(0, 0, At, B0); PG8_MMA(0, 1, At, B1); PG8_BAR; PG8_SCHED;
;             PG8_LDA(At, 0, 1); PG8_STAGE(PG8_SB(0, 0), b2, voffB); PG8_STAGE(PG8_SB(0, 1), b2 + hstep, voffB); PG8_STAGE(PG8_SA(0, 0), a2, voffA);
;             PG8_WAIT_V(8); PG8_WAIT_L(0); PG8_BAR; PG8_MMA(1, 0, At, B0); PG8_MMA(1, 1, At, B1); PG8_BAR; PG8_SCHED;
;             PG8_LDB(B0, 1, 0); PG8_LDB(B1, 1, 1); PG8_SCHED; PG8_LDA(At, 1, 0); PG8_STAGE(PG8_SA(0, 1), a2 + hstep, voffA);
;             PG8_WAIT_V(8); PG8_WAIT_L(0); PG8_BAR; PG8_MMA(0, 0, At, B0); PG8_MMA(0, 1, At, B1); PG8_BAR; PG8_SCHED;
;             PG8_LDA(At, 1, 1); PG8_STAGE(PG8_SB(1, 0), b3, voffB); PG8_STAGE(PG8_SB(1, 1), b3 + hstep, voffB); PG8_STAGE(PG8_SA(1, 0), a3, voffA);
;             PG8_WAIT_V(8); PG8_WAIT_L(0); PG8_BAR; PG8_MMA(1, 0, At, B0); PG8_MMA(1, 1, At, B1); PG8_BAR; PG8_SCHED;
	s_add_i32 s46, s52, s0
	s_add_u32 s100, s44, s28
	s_addc_u32 s101, s45, s29
	s_mov_b32 m0, s46
	ds_read_b128 v[172:175], v192 offset:49152
	ds_read_b128 v[194:197], v192 offset:50176
	ds_read_b128 v[198:201], v192 offset:51200
	ds_read_b128 v[202:205], v192 offset:52224
	ds_read_b128 v[206:209], v192 offset:53248
	ds_read_b128 v[210:213], v192 offset:54272
	ds_read_b128 v[214:217], v192 offset:55296
	ds_read_b128 v[218:221], v192 offset:56320
	global_load_lds_dwordx4 v176, s[100:101]
	s_add_i32 m0, s46, 0x2000
	s_add_u32 s44, s44, 0x80080
	s_addc_u32 s45, s45, 0
	s_add_i32 s46, s53, s0
	global_load_lds_dwordx4 v136, s[100:101]
	s_mov_b32 m0, s46
	s_nop 0
	global_load_lds_dwordx4 v176, s[44:45]
	s_add_i32 m0, s46, 0x2000
	s_nop 0
	global_load_lds_dwordx4 v136, s[44:45]
	v_lshl_add_u64 v[178:179], v[182:183], 0, s[28:29]
	s_mov_b32 m0, s25
	s_nop 0
	global_load_lds_dwordx4 v[178:179], off
	v_lshl_add_u64 v[178:179], v[184:185], 0, s[28:29]
	s_mov_b32 m0, s27
	s_nop 0
	global_load_lds_dwordx4 v[178:179], off
	s_waitcnt vmcnt(8)
	s_waitcnt lgkmcnt(0)
	s_barrier
	s_setprio 1
	s_waitcnt lgkmcnt(0)
	v_mfma_f32_16x16x32_bf16 v[60:63], v[128:131], v[172:175], v[60:63]
	v_mfma_f32_16x16x32_bf16 v[56:59], v[148:151], v[172:175], v[56:59]
	v_mfma_f32_16x16x32_bf16 v[48:51], v[128:131], v[198:201], v[48:51]
	v_mfma_f32_16x16x32_bf16 v[40:43], v[148:151], v[198:201], v[40:43]
	v_mfma_f32_16x16x32_bf16 v[32:35], v[128:131], v[206:209], v[32:35]
	v_mfma_f32_16x16x32_bf16 v[24:27], v[148:151], v[206:209], v[24:27]
	v_mfma_f32_16x16x32_bf16 v[16:19], v[128:131], v[214:217], v[16:19]
	v_mfma_f32_16x16x32_bf16 v[8:11], v[148:151], v[214:217], v[8:11]
	v_mfma_f32_16x16x32_bf16 v[60:63], v[132:135], v[194:197], v[60:63]
	v_mfma_f32_16x16x32_bf16 v[56:59], v[152:155], v[194:197], v[56:59]
	v_mfma_f32_16x16x32_bf16 v[48:51], v[132:135], v[202:205], v[48:51]
	v_mfma_f32_16x16x32_bf16 v[40:43], v[152:155], v[202:205], v[40:43]
	v_mfma_f32_16x16x32_bf16 v[32:35], v[132:135], v[210:213], v[32:35]
	v_mfma_f32_16x16x32_bf16 v[24:27], v[152:155], v[210:213], v[24:27]
	v_mfma_f32_16x16x32_bf16 v[16:19], v[132:135], v[218:221], v[16:19]
	v_mfma_f32_16x16x32_bf16 v[8:11], v[152:155], v[218:221], v[8:11]
	s_setprio 0
	s_setprio 1
	v_mfma_f32_16x16x32_bf16 v[52:55], v[156:159], v[172:175], v[52:55]
	v_mfma_f32_16x16x32_bf16 v[44:47], v[164:167], v[172:175], v[44:47]
	v_mfma_f32_16x16x32_bf16 v[36:39], v[156:159], v[198:201], v[36:39]
	v_mfma_f32_16x16x32_bf16 v[28:31], v[164:167], v[198:201], v[28:31]
	v_mfma_f32_16x16x32_bf16 v[20:23], v[156:159], v[206:209], v[20:23]
	v_mfma_f32_16x16x32_bf16 v[12:15], v[164:167], v[206:209], v[12:15]
	v_mfma_f32_16x16x32_bf16 v[4:7], v[156:159], v[214:217], v[4:7]
	v_mfma_f32_16x16x32_bf16 v[0:3], v[164:167], v[214:217], v[0:3]
	v_mfma_f32_16x16x32_bf16 v[52:55], v[160:163], v[194:197], v[52:55]
	v_mfma_f32_16x16x32_bf16 v[44:47], v[168:171], v[194:197], v[44:47]
	v_mfma_f32_16x16x32_bf16 v[36:39], v[160:163], v[202:205], v[36:39]
	v_mfma_f32_16x16x32_bf16 v[28:31], v[168:171], v[202:205], v[28:31]
	v_mfma_f32_16x16x32_bf16 v[20:23], v[160:163], v[210:213], v[20:23]
	v_mfma_f32_16x16x32_bf16 v[12:15], v[168:171], v[210:213], v[12:15]
	v_mfma_f32_16x16x32_bf16 v[4:7], v[160:163], v[218:221], v[4:7]
	v_mfma_f32_16x16x32_bf16 v[0:3], v[168:171], v[218:221], v[0:3]
	s_setprio 0
	s_barrier
	s_add_i32 s51, s51, 2
	s_add_u32 s34, s34, 0x100
	s_addc_u32 s35, s35, 0
	s_add_u32 s49, s49, 0x100
	s_addc_u32 s50, s50, 0
	s_cmp_gt_u32 s51, 29
	s_cbranch_scc0 .LBB0_120
	s_and_b64 vcc, exec, s[14:15]
	s_cbranch_vccz .LBB0_123
	s_barrier

; #define PG8_STAGE(bufoff, gbase, voff) do { _Pragma("unroll") for (int _i = 0; _i < 2; ++_i) \
;         __builtin_amdgcn_global_load_lds((const unsigned*)((const char*)(gbase) + (voff)[_i]), (PG8_LAS unsigned*)(lds + (bufoff) + ldsw + _i * 8192), 16, 0, 0); } while (0)
; #define PG8_LDA(dst, b, h) do { _Pragma("unroll") for (int m = 0; m < 4; ++m) _Pragma("unroll") for (int k = 0; k < 2; ++k) dst[m][k] = *(const PG8_LAS bf16x8*)(lds + PG8_SA(b, h) + aoff + m * 2048 + k * 1024); } while (0)
; #define PG8_LDB(dst, b, h) do { _Pragma("unroll") for (int n = 0; n < 2; ++n) _Pragma("unroll") for (int k = 0; k < 2; ++k) dst[n][k] = *(const PG8_LAS bf16x8*)(lds + PG8_SB(b, h) + boff + n * 2048 + k * 1024); } while (0)
; #define PG8_MMA(ai, bj, At, Bt) do { __builtin_amdgcn_s_setprio(1); _Pragma("unroll") for (int m = 0; m < 4; ++m) _Pragma("unroll") for (int n = 0; n < 2; ++n) _Pragma("unroll") for (int k = 0; k < 2; ++k) \
;         acc[ai][bj][m][n] = __builtin_amdgcn_mfma_f32_16x16x32_bf16(Bt[n][k], At[m][k], acc[ai][bj][m][n], 0, 0, 0); __builtin_amdgcn_s_setprio(0); } while (0)
; #define PG8_WAIT_V(n) asm volatile("s_waitcnt vmcnt(" #n ")" ::: "memory")
; #define PG8_BAR __builtin_amdgcn_s_barrier()
; template <class Epi, class Sched, bool ALIGN_EPI = false, bool SP2 = false>
; __device__ __forceinline__ void gemm_phase(PG8_LAS unsigned char* lds, const Gemm g, const Sched& S, const Epi& E, int wv) {
;     ...
;         for (int t = 0; t < nt; t += 2) {
;             const bool last = (t == nt - 2);
;             const char* a1 = cA + (size_t)(t + 1) * kstep;
;             const char* a2 = last ? nA : cA + (size_t)(t + 2) * kstep; const char* b2 = last ? nB : cB + (size_t)(t + 2) * kstep;
;             const char* a3 = a2 + kstep; const char* b3 = b2 + kstep;
;             if (last && has_next) S.a_ready(nxt);
;             if constexpr (SP2) {
;             PG8_LDB(B0, 0, 0); PG8_LDB(B1, 0, 1); PG8_SCHED; PG8_LDA(At, 0, 0); PG8_STAGE(PG8_SA(1, 1), a1 + hstep, voffA);
;             PG8_WAIT_V(8); PG8_WAIT_L(0); PG8_BAR; PG8_MMA(0, 0, At, B0); PG8_MMA(0, 1, At, B1); PG8_BAR; PG8_SCHED;
;             PG8_LDA(At, 0, 1); PG8_STAGE(PG8_SB(0, 0), b2, voffB); PG8_STAGE(PG8_SB(0, 1), b2 + hstep, voffB); PG8_STAGE(PG8_SA(0, 0), a2, voffA);
;             PG8_WAIT_V(8); PG8_WAIT_L(0); PG8_BAR; PG8_MMA(1, 0, At, B0); PG8_MMA(1, 1, At, B1); PG8_BAR; PG8_SCHED;
.LBB0_343:
	s_add_u32 s48, s40, 0xfff80080
	s_addc_u32 s49, s41, -1
	s_add_i32 s55, 0, 0x10000
	s_cmp_eq_u32 s54, 28
	s_cselect_b32 s51, s7, s49
	s_cselect_b32 s50, s21, s48
	s_cselect_b32 s49, s19, s53
	s_cselect_b32 s48, s35, s52
	s_add_i32 s58, 0, 0x14000
	v_add_u32_e32 v154, s55, v147
	v_add_u32_e32 v170, s58, v147
	ds_read_b128 v[138:141], v154
	ds_read_b128 v[142:145], v154 offset:1024
	ds_read_b128 v[150:153], v154 offset:2048
	s_nop 0
	ds_read_b128 v[154:157], v154 offset:3072
	ds_read_b128 v[158:161], v170
	ds_read_b128 v[162:165], v170 offset:1024
	ds_read_b128 v[166:169], v170 offset:2048
	ds_read_b128 v[170:173], v170 offset:3072
	s_add_i32 m0, s3, 0xc000
	ds_read_b128 v[178:181], v149
	ds_read_b128 v[182:185], v149 offset:1024
	ds_read_b128 v[186:189], v149 offset:2048
	ds_read_b128 v[190:193], v149 offset:3072
	ds_read_b128 v[194:197], v149 offset:4096
	ds_read_b128 v[198:201], v149 offset:5120
	ds_read_b128 v[202:205], v149 offset:6144
	ds_read_b128 v[206:209], v149 offset:7168
	global_load_lds_dwordx4 v134, s[40:41]
	s_add_i32 m0, s3, 0xe000
	s_nop 0
	global_load_lds_dwordx4 v136, s[40:41]
	s_waitcnt vmcnt(8)
	s_waitcnt lgkmcnt(0)
	s_barrier
	s_setprio 1
	s_waitcnt lgkmcnt(0)
	v_mfma_f32_16x16x32_bf16 v[124:127], v[138:141], v[178:181], v[124:127]
	v_mfma_f32_16x16x32_bf16 v[120:123], v[150:153], v[178:181], v[120:123]
	v_mfma_f32_16x16x32_bf16 v[108:111], v[138:141], v[186:189], v[108:111]
	v_mfma_f32_16x16x32_bf16 v[104:107], v[150:153], v[186:189], v[104:107]
	v_mfma_f32_16x16x32_bf16 v[92:95], v[138:141], v[194:197], v[92:95]
	v_mfma_f32_16x16x32_bf16 v[88:91], v[150:153], v[194:197], v[88:91]
	v_mfma_f32_16x16x32_bf16 v[76:79], v[138:141], v[202:205], v[76:79]
	v_mfma_f32_16x16x32_bf16 v[72:75], v[150:153], v[202:205], v[72:75]
	v_mfma_f32_16x16x32_bf16 v[124:127], v[142:145], v[182:185], v[124:127]
	v_mfma_f32_16x16x32_bf16 v[120:123], v[154:157], v[182:185], v[120:123]
	v_mfma_f32_16x16x32_bf16 v[108:111], v[142:145], v[190:193], v[108:111]
	v_mfma_f32_16x16x32_bf16 v[104:107], v[154:157], v[190:193], v[104:107]
	v_mfma_f32_16x16x32_bf16 v[92:95], v[142:145], v[198:201], v[92:95]
	v_mfma_f32_16x16x32_bf16 v[88:91], v[154:157], v[198:201], v[88:91]
	v_mfma_f32_16x16x32_bf16 v[76:79], v[142:145], v[206:209], v[76:79]
	v_mfma_f32_16x16x32_bf16 v[72:75], v[154:157], v[206:209], v[72:75]
	s_setprio 0
	s_setprio 1
	v_mfma_f32_16x16x32_bf16 v[116:119], v[158:161], v[178:181], v[116:119]
	v_mfma_f32_16x16x32_bf16 v[112:115], v[166:169], v[178:181], v[112:115]
	v_mfma_f32_16x16x32_bf16 v[100:103], v[158:161], v[186:189], v[100:103]
	v_mfma_f32_16x16x32_bf16 v[96:99], v[166:169], v[186:189], v[96:99]
	v_mfma_f32_16x16x32_bf16 v[84:87], v[158:161], v[194:197], v[84:87]
	v_mfma_f32_16x16x32_bf16 v[80:83], v[166:169], v[194:197], v[80:83]
	v_mfma_f32_16x16x32_bf16 v[68:71], v[158:161], v[202:205], v[68:71]
	v_mfma_f32_16x16x32_bf16 v[64:67], v[166:169], v[202:205], v[64:67]
	v_mfma_f32_16x16x32_bf16 v[116:119], v[162:165], v[182:185], v[116:119]
	v_mfma_f32_16x16x32_bf16 v[112:115], v[170:173], v[182:185], v[112:115]
	v_mfma_f32_16x16x32_bf16 v[100:103], v[162:165], v[190:193], v[100:103]
	v_mfma_f32_16x16x32_bf16 v[96:99], v[170:173], v[190:193], v[96:99]
	v_mfma_f32_16x16x32_bf16 v[84:87], v[162:165], v[198:201], v[84:87]
	v_mfma_f32_16x16x32_bf16 v[80:83], v[170:173], v[198:201], v[80:83]
	v_mfma_f32_16x16x32_bf16 v[68:71], v[162:165], v[206:209], v[68:71]
	v_mfma_f32_16x16x32_bf16 v[64:67], v[170:173], v[206:209], v[64:67]
	s_setprio 0
	s_barrier
	s_add_i32 s55, s55, s2
	s_mov_b32 m0, s55
	ds_read_b128 v[178:181], v149 offset:16384
	ds_read_b128 v[182:185], v149 offset:17408
	ds_read_b128 v[186:189], v149 offset:18432
	ds_read_b128 v[190:193], v149 offset:19456
	ds_read_b128 v[194:197], v149 offset:20480
	ds_read_b128 v[198:201], v149 offset:21504
	ds_read_b128 v[202:205], v149 offset:22528
	ds_read_b128 v[206:209], v149 offset:23552
	global_load_lds_dwordx4 v176, s[48:49]
	s_add_i32 m0, s55, 0x2000
	s_add_u32 s56, s48, 0x80000
	s_addc_u32 s57, s49, 0
	s_add_i32 s55, s58, s2
	global_load_lds_dwordx4 v132, s[48:49]
	s_mov_b32 m0, s55
	v_lshl_add_u64 v[214:215], s[50:51], 0, v[130:131]
	global_load_lds_dwordx4 v176, s[56:57]
	s_add_i32 m0, s55, 0x2000
	s_nop 0
	global_load_lds_dwordx4 v132, s[56:57]
	v_lshl_add_u64 v[212:213], s[50:51], 0, v[128:129]
	s_mov_b32 m0, s3
	s_nop 0
	global_load_lds_dwordx4 v[212:213], off
	s_mov_b32 m0, s22
	s_nop 0
	global_load_lds_dwordx4 v[214:215], off
	s_waitcnt vmcnt(8)
	s_waitcnt lgkmcnt(0)
	s_barrier
; #define PG8_STAGE(bufoff, gbase, voff) do { _Pragma("unroll") for (int _i = 0; _i < 2; ++_i) \
;         __builtin_amdgcn_global_load_lds((const unsigned*)((const char*)(gbase) + (voff)[_i]), (PG8_LAS unsigned*)(lds + (bufoff) + ldsw + _i * 8192), 16, 0, 0); } while (0)
; #define PG8_LDA(dst, b, h) do { _Pragma("unroll") for (int m = 0; m < 4; ++m) _Pragma("unroll") for (int k = 0; k < 2; ++k) dst[m][k] = *(const PG8_LAS bf16x8*)(lds + PG8_SA(b, h) + aoff + m * 2048 + k * 1024); } while (0)
; #define PG8_LDB(dst, b, h) do { _Pragma("unroll") for (int n = 0; n < 2; ++n) _Pragma("unroll") for (int k = 0; k < 2; ++k) dst[n][k] = *(const PG8_LAS bf16x8*)(lds + PG8_SB(b, h) + boff + n * 2048 + k * 1024); } while (0)
; #define PG8_MMA(ai, bj, At, Bt) do { __builtin_amdgcn_s_setprio(1); _Pragma("unroll") for (int m = 0; m < 4; ++m) _Pragma("unroll") for (int n = 0; n < 2; ++n) _Pragma("unroll") for (int k = 0; k < 2; ++k) \
;         acc[ai][bj][m][n] = __builtin_amdgcn_mfma_f32_16x16x32_bf16(Bt[n][k], At[m][k], acc[ai][bj][m][n], 0, 0, 0); __builtin_amdgcn_s_setprio(0); } while (0)
; #define PG8_WAIT_V(n) asm volatile("s_waitcnt vmcnt(" #n ")" ::: "memory")
; #define PG8_WAIT_L(n) asm volatile("s_waitcnt lgkmcnt(" #n ")" ::: "memory")
; #define PG8_BAR __builtin_amdgcn_s_barrier()
; #define PG8_SCHED __builtin_amdgcn_sched_barrier(0)
; template <class Epi, class Sched, bool ALIGN_EPI = false, bool SP2 = false>
; __device__ __forceinline__ void gemm_phase(PG8_LAS unsigned char* lds, const Gemm g, const Sched& S, const Epi& E, int wv) {
;     ...
;             PG8_WAIT_V(8); PG8_WAIT_L(0); PG8_BAR; PG8_MMA(1, 0, At, B0); PG8_MMA(1, 1, At, B1); PG8_BAR; PG8_SCHED;
;             PG8_LDB(B0, 1, 0); PG8_LDB(B1, 1, 1); PG8_SCHED; PG8_LDA(At, 1, 0); PG8_STAGE(PG8_SA(0, 1), a2 + hstep, voffA);
;             PG8_WAIT_V(8); PG8_WAIT_L(0); PG8_BAR; PG8_MMA(0, 0, At, B0); PG8_MMA(0, 1, At, B1); PG8_BAR; PG8_SCHED;
	s_setprio 1
	s_waitcnt lgkmcnt(0)
	v_mfma_f32_16x16x32_bf16 v[60:63], v[138:141], v[178:181], v[60:63]
	v_mfma_f32_16x16x32_bf16 v[56:59], v[150:153], v[178:181], v[56:59]
	v_mfma_f32_16x16x32_bf16 v[44:47], v[138:141], v[186:189], v[44:47]
	v_mfma_f32_16x16x32_bf16 v[40:43], v[150:153], v[186:189], v[40:43]
	v_mfma_f32_16x16x32_bf16 v[28:31], v[138:141], v[194:197], v[28:31]
	v_mfma_f32_16x16x32_bf16 v[24:27], v[150:153], v[194:197], v[24:27]
	v_mfma_f32_16x16x32_bf16 v[12:15], v[138:141], v[202:205], v[12:15]
	v_mfma_f32_16x16x32_bf16 v[8:11], v[150:153], v[202:205], v[8:11]
	v_mfma_f32_16x16x32_bf16 v[60:63], v[142:145], v[182:185], v[60:63]
	v_mfma_f32_16x16x32_bf16 v[56:59], v[154:157], v[182:185], v[56:59]
	v_mfma_f32_16x16x32_bf16 v[44:47], v[142:145], v[190:193], v[44:47]
	v_mfma_f32_16x16x32_bf16 v[40:43], v[154:157], v[190:193], v[40:43]
	v_mfma_f32_16x16x32_bf16 v[28:31], v[142:145], v[198:201], v[28:31]
	v_mfma_f32_16x16x32_bf16 v[24:27], v[154:157], v[198:201], v[24:27]
	v_mfma_f32_16x16x32_bf16 v[12:15], v[142:145], v[206:209], v[12:15]
	v_mfma_f32_16x16x32_bf16 v[8:11], v[154:157], v[206:209], v[8:11]
	s_setprio 0
	s_setprio 1
	v_mfma_f32_16x16x32_bf16 v[52:55], v[158:161], v[178:181], v[52:55]
	v_mfma_f32_16x16x32_bf16 v[48:51], v[166:169], v[178:181], v[48:51]
	v_mfma_f32_16x16x32_bf16 v[36:39], v[158:161], v[186:189], v[36:39]
	v_mfma_f32_16x16x32_bf16 v[32:35], v[166:169], v[186:189], v[32:35]
	v_mfma_f32_16x16x32_bf16 v[20:23], v[158:161], v[194:197], v[20:23]
	v_mfma_f32_16x16x32_bf16 v[16:19], v[166:169], v[194:197], v[16:19]
	v_mfma_f32_16x16x32_bf16 v[4:7], v[158:161], v[202:205], v[4:7]
	v_mfma_f32_16x16x32_bf16 v[0:3], v[166:169], v[202:205], v[0:3]
	v_mfma_f32_16x16x32_bf16 v[52:55], v[162:165], v[182:185], v[52:55]
	v_mfma_f32_16x16x32_bf16 v[48:51], v[170:173], v[182:185], v[48:51]
	v_mfma_f32_16x16x32_bf16 v[36:39], v[162:165], v[190:193], v[36:39]
	v_mfma_f32_16x16x32_bf16 v[32:35], v[170:173], v[190:193], v[32:35]
	v_mfma_f32_16x16x32_bf16 v[20:23], v[162:165], v[198:201], v[20:23]
	v_mfma_f32_16x16x32_bf16 v[16:19], v[170:173], v[198:201], v[16:19]
	v_mfma_f32_16x16x32_bf16 v[4:7], v[162:165], v[206:209], v[4:7]
	v_mfma_f32_16x16x32_bf16 v[0:3], v[170:173], v[206:209], v[0:3]
	s_setprio 0
	s_barrier
	s_add_i32 s55, 0, 0x18000
	s_add_i32 s56, 0, 0x1c000
	v_add_u32_e32 v154, s55, v147
	v_add_u32_e32 v170, s56, v147
	ds_read_b128 v[138:141], v154
	ds_read_b128 v[142:145], v154 offset:1024
	ds_read_b128 v[150:153], v154 offset:2048
	ds_read_b128 v[154:157], v154 offset:3072
	ds_read_b128 v[158:161], v170
	ds_read_b128 v[162:165], v170 offset:1024
	ds_read_b128 v[166:169], v170 offset:2048
	ds_read_b128 v[170:173], v170 offset:3072
	s_add_u32 s50, s50, 0x80000
	s_addc_u32 s51, s51, 0
	s_mov_b32 m0, s23
	ds_read_b128 v[178:181], v149 offset:32768
	ds_read_b128 v[182:185], v149 offset:33792
	ds_read_b128 v[186:189], v149 offset:34816
	ds_read_b128 v[190:193], v149 offset:35840
	ds_read_b128 v[194:197], v149 offset:36864
	ds_read_b128 v[198:201], v149 offset:37888
	ds_read_b128 v[202:205], v149 offset:38912
	ds_read_b128 v[206:209], v149 offset:39936
	global_load_lds_dwordx4 v128, s[50:51]
	v_lshl_add_u64 v[216:217], s[50:51], 0, v[130:131]
	s_mov_b32 m0, s24
	s_nop 0
	global_load_lds_dwordx4 v[216:217], off
	s_waitcnt vmcnt(8)
	s_waitcnt lgkmcnt(0)
	s_barrier
	s_setprio 1
	s_waitcnt lgkmcnt(0)
	v_mfma_f32_16x16x32_bf16 v[124:127], v[138:141], v[178:181], v[124:127]
	v_mfma_f32_16x16x32_bf16 v[120:123], v[150:153], v[178:181], v[120:123]
	v_mfma_f32_16x16x32_bf16 v[108:111], v[138:141], v[186:189], v[108:111]
	v_mfma_f32_16x16x32_bf16 v[104:107], v[150:153], v[186:189], v[104:107]
	v_mfma_f32_16x16x32_bf16 v[92:95], v[138:141], v[194:197], v[92:95]
	v_mfma_f32_16x16x32_bf16 v[88:91], v[150:153], v[194:197], v[88:91]
	v_mfma_f32_16x16x32_bf16 v[76:79], v[138:141], v[202:205], v[76:79]
	v_mfma_f32_16x16x32_bf16 v[72:75], v[150:153], v[202:205], v[72:75]
	v_mfma_f32_16x16x32_bf16 v[124:127], v[142:145], v[182:185], v[124:127]
	v_mfma_f32_16x16x32_bf16 v[120:123], v[154:157], v[182:185], v[120:123]
	v_mfma_f32_16x16x32_bf16 v[108:111], v[142:145], v[190:193], v[108:111]
	v_mfma_f32_16x16x32_bf16 v[104:107], v[154:157], v[190:193], v[104:107]
	v_mfma_f32_16x16x32_bf16 v[92:95], v[142:145], v[198:201], v[92:95]
	v_mfma_f32_16x16x32_bf16 v[88:91], v[154:157], v[198:201], v[88:91]
	v_mfma_f32_16x16x32_bf16 v[76:79], v[142:145], v[206:209], v[76:79]
	v_mfma_f32_16x16x32_bf16 v[72:75], v[154:157], v[206:209], v[72:75]
	s_setprio 0
	s_setprio 1
	v_mfma_f32_16x16x32_bf16 v[116:119], v[158:161], v[178:181], v[116:119]
	v_mfma_f32_16x16x32_bf16 v[112:115], v[166:169], v[178:181], v[112:115]
	v_mfma_f32_16x16x32_bf16 v[100:103], v[158:161], v[186:189], v[100:103]
	v_mfma_f32_16x16x32_bf16 v[96:99], v[166:169], v[186:189], v[96:99]
	v_mfma_f32_16x16x32_bf16 v[84:87], v[158:161], v[194:197], v[84:87]
	v_mfma_f32_16x16x32_bf16 v[80:83], v[166:169], v[194:197], v[80:83]
	v_mfma_f32_16x16x32_bf16 v[68:71], v[158:161], v[202:205], v[68:71]
	v_mfma_f32_16x16x32_bf16 v[64:67], v[166:169], v[202:205], v[64:67]
	v_mfma_f32_16x16x32_bf16 v[116:119], v[162:165], v[182:185], v[116:119]
	v_mfma_f32_16x16x32_bf16 v[112:115], v[170:173], v[182:185], v[112:115]
	v_mfma_f32_16x16x32_bf16 v[100:103], v[162:165], v[190:193], v[100:103]
	v_mfma_f32_16x16x32_bf16 v[96:99], v[170:173], v[190:193], v[96:99]
	v_mfma_f32_16x16x32_bf16 v[84:87], v[162:165], v[198:201], v[84:87]
	v_mfma_f32_16x16x32_bf16 v[80:83], v[170:173], v[198:201], v[80:83]
	v_mfma_f32_16x16x32_bf16 v[68:71], v[162:165], v[206:209], v[68:71]
	v_mfma_f32_16x16x32_bf16 v[64:67], v[170:173], v[206:209], v[64:67]
	s_setprio 0
	s_barrier
; #define PG8_STAGE(bufoff, gbase, voff) do { _Pragma("unroll") for (int _i = 0; _i < 2; ++_i) \
;         __builtin_amdgcn_global_load_lds((const unsigned*)((const char*)(gbase) + (voff)[_i]), (PG8_LAS unsigned*)(lds + (bufoff) + ldsw + _i * 8192), 16, 0, 0); } while (0)
; #define PG8_LDA(dst, b, h) do { _Pragma("unroll") for (int m = 0; m < 4; ++m) _Pragma("unroll") for (int k = 0; k < 2; ++k) dst[m][k] = *(const PG8_LAS bf16x8*)(lds + PG8_SA(b, h) + aoff + m * 2048 + k * 1024); } while (0)
; #define PG8_LDB(dst, b, h) do { _Pragma("unroll") for (int n = 0; n < 2; ++n) _Pragma("unroll") for (int k = 0; k < 2; ++k) dst[n][k] = *(const PG8_LAS bf16x8*)(lds + PG8_SB(b, h) + boff + n * 2048 + k * 1024); } while (0)
; template <class Epi, class Sched, bool ALIGN_EPI = false, bool SP2 = false>
; __device__ __forceinline__ void gemm_phase(PG8_LAS unsigned char* lds, const Gemm g, const Sched& S, const Epi& E, int wv) {
;     ...
;         for (int t = 0; t < nt; t += 2) {
;             const bool last = (t == nt - 2);
;             const char* a1 = cA + (size_t)(t + 1) * kstep;
;             const char* a2 = last ? nA : cA + (size_t)(t + 2) * kstep; const char* b2 = last ? nB : cB + (size_t)(t + 2) * kstep;
;             const char* a3 = a2 + kstep; const char* b3 = b2 + kstep;
;             if (last && has_next) S.a_ready(nxt);
;             if constexpr (SP2) {
;             PG8_LDB(B0, 0, 0); PG8_LDB(B1, 0, 1); PG8_SCHED; PG8_LDA(At, 0, 0); PG8_STAGE(PG8_SA(1, 1), a1 + hstep, voffA);
;             PG8_WAIT_V(8); PG8_WAIT_L(0); PG8_BAR; PG8_MMA(0, 0, At, B0); PG8_MMA(0, 1, At, B1); PG8_BAR; PG8_SCHED;
;             PG8_LDA(At, 0, 1); PG8_STAGE(PG8_SB(0, 0), b2, voffB); PG8_STAGE(PG8_SB(0, 1), b2 + hstep, voffB); PG8_STAGE(PG8_SA(0, 0), a2, voffA);
;             PG8_WAIT_V(8); PG8_WAIT_L(0); PG8_BAR; PG8_MMA(1, 0, At, B0); PG8_MMA(1, 1, At, B1); PG8_BAR; PG8_SCHED;
;             PG8_LDB(B0, 1, 0); PG8_LDB(B1, 1, 1); PG8_SCHED; PG8_LDA(At, 1, 0); PG8_STAGE(PG8_SA(0, 1), a2 + hstep, voffA);
;             PG8_WAIT_V(8); PG8_WAIT_L(0); PG8_BAR; PG8_MMA(0, 0, At, B0); PG8_MMA(0, 1, At, B1); PG8_BAR; PG8_SCHED;
;             PG8_LDA(At, 1, 1); PG8_STAGE(PG8_SB(1, 0), b3, voffB); PG8_STAGE(PG8_SB(1, 1), b3 + hstep, voffB); PG8_STAGE(PG8_SA(1, 0), a3, voffA);
;             PG8_WAIT_V(8); PG8_WAIT_L(0); PG8_BAR; PG8_MMA(1, 0, At, B0); PG8_MMA(1, 1, At, B1); PG8_BAR; PG8_SCHED;
	s_add_i32 s50, s55, s2
	s_add_u32 s100, s48, s28
	s_addc_u32 s101, s49, s29
	s_mov_b32 m0, s50
	ds_read_b128 v[178:181], v149 offset:49152
	ds_read_b128 v[182:185], v149 offset:50176
	ds_read_b128 v[186:189], v149 offset:51200
	ds_read_b128 v[190:193], v149 offset:52224
	ds_read_b128 v[194:197], v149 offset:53248
	ds_read_b128 v[198:201], v149 offset:54272
	ds_read_b128 v[202:205], v149 offset:55296
	ds_read_b128 v[206:209], v149 offset:56320
	global_load_lds_dwordx4 v176, s[100:101]
	s_add_i32 m0, s50, 0x2000
	s_add_u32 s48, s48, 0x80080
	s_addc_u32 s49, s49, 0
	s_add_i32 s50, s56, s2
	global_load_lds_dwordx4 v132, s[100:101]
	s_mov_b32 m0, s50
	s_nop 0
	global_load_lds_dwordx4 v176, s[48:49]
	s_add_i32 m0, s50, 0x2000
	s_nop 0
	global_load_lds_dwordx4 v132, s[48:49]
	v_lshl_add_u64 v[174:175], v[212:213], 0, s[28:29]
	s_mov_b32 m0, s27
	s_nop 0
	global_load_lds_dwordx4 v[174:175], off
	v_lshl_add_u64 v[174:175], v[214:215], 0, s[28:29]
	s_mov_b32 m0, s30
	s_nop 0
	global_load_lds_dwordx4 v[174:175], off
	s_waitcnt vmcnt(8)
	s_waitcnt lgkmcnt(0)
	s_barrier
	s_setprio 1
	s_waitcnt lgkmcnt(0)
	v_mfma_f32_16x16x32_bf16 v[60:63], v[138:141], v[178:181], v[60:63]
	v_mfma_f32_16x16x32_bf16 v[56:59], v[150:153], v[178:181], v[56:59]
	v_mfma_f32_16x16x32_bf16 v[44:47], v[138:141], v[186:189], v[44:47]
	v_mfma_f32_16x16x32_bf16 v[40:43], v[150:153], v[186:189], v[40:43]
	v_mfma_f32_16x16x32_bf16 v[28:31], v[138:141], v[194:197], v[28:31]
	v_mfma_f32_16x16x32_bf16 v[24:27], v[150:153], v[194:197], v[24:27]
	v_mfma_f32_16x16x32_bf16 v[12:15], v[138:141], v[202:205], v[12:15]
	v_mfma_f32_16x16x32_bf16 v[8:11], v[150:153], v[202:205], v[8:11]
	v_mfma_f32_16x16x32_bf16 v[60:63], v[142:145], v[182:185], v[60:63]
	v_mfma_f32_16x16x32_bf16 v[56:59], v[154:157], v[182:185], v[56:59]
	v_mfma_f32_16x16x32_bf16 v[44:47], v[142:145], v[190:193], v[44:47]
	v_mfma_f32_16x16x32_bf16 v[40:43], v[154:157], v[190:193], v[40:43]
	v_mfma_f32_16x16x32_bf16 v[28:31], v[142:145], v[198:201], v[28:31]
	v_mfma_f32_16x16x32_bf16 v[24:27], v[154:157], v[198:201], v[24:27]
	v_mfma_f32_16x16x32_bf16 v[12:15], v[142:145], v[206:209], v[12:15]
	v_mfma_f32_16x16x32_bf16 v[8:11], v[154:157], v[206:209], v[8:11]
	s_setprio 0
	s_setprio 1
	v_mfma_f32_16x16x32_bf16 v[52:55], v[158:161], v[178:181], v[52:55]
	v_mfma_f32_16x16x32_bf16 v[48:51], v[166:169], v[178:181], v[48:51]
	v_mfma_f32_16x16x32_bf16 v[36:39], v[158:161], v[186:189], v[36:39]
	v_mfma_f32_16x16x32_bf16 v[32:35], v[166:169], v[186:189], v[32:35]
	v_mfma_f32_16x16x32_bf16 v[20:23], v[158:161], v[194:197], v[20:23]
	v_mfma_f32_16x16x32_bf16 v[16:19], v[166:169], v[194:197], v[16:19]
	v_mfma_f32_16x16x32_bf16 v[4:7], v[158:161], v[202:205], v[4:7]
	v_mfma_f32_16x16x32_bf16 v[0:3], v[166:169], v[202:205], v[0:3]
	v_mfma_f32_16x16x32_bf16 v[52:55], v[162:165], v[182:185], v[52:55]
	v_mfma_f32_16x16x32_bf16 v[48:51], v[170:173], v[182:185], v[48:51]
	v_mfma_f32_16x16x32_bf16 v[36:39], v[162:165], v[190:193], v[36:39]
	v_mfma_f32_16x16x32_bf16 v[32:35], v[170:173], v[190:193], v[32:35]
	v_mfma_f32_16x16x32_bf16 v[20:23], v[162:165], v[198:201], v[20:23]
	v_mfma_f32_16x16x32_bf16 v[16:19], v[170:173], v[198:201], v[16:19]
	v_mfma_f32_16x16x32_bf16 v[4:7], v[162:165], v[206:209], v[4:7]
	v_mfma_f32_16x16x32_bf16 v[0:3], v[170:173], v[206:209], v[0:3]
	s_setprio 0
	s_barrier
	s_add_i32 s54, s54, 2
	s_add_u32 s40, s40, 0x100
	s_addc_u32 s41, s41, 0
	s_add_u32 s52, s52, 0x100
	s_addc_u32 s53, s53, 0
	s_cmp_gt_u32 s54, 29
	s_cbranch_scc0 .LBB0_343
	s_and_b64 vcc, exec, s[16:17]
	s_cbranch_vccz .LBB0_346
	s_barrier
